# chain (DN/SSD) step compute: rotating-buffer pipelining of LDS fragment reads with counted lgkmcnt
# baseline (speedup 1.0000x reference)
.LBB0_320:
	s_and_b64 s[6:7], s[38:39], exec
	s_cselect_b32 s6, s19, s16
	s_bitcmp1_b32 s19, 0
	s_cselect_b32 s7, 0x4400, 0
	v_add_u32_e32 v234, s7, v133
	ds_read_b128 v[230:233], v234
	ds_read_b128 v[236:239], v234 offset:64
	ds_read_b128 v[248:251], v234 offset:128
	ds_read_b128 v[252:255], v234 offset:192
	v_cvt_pk_bf16_f32 v60, v0, v1
	v_cvt_pk_bf16_f32 v61, v2, v3
	v_cvt_pk_bf16_f32 v62, v28, v29
	v_cvt_pk_bf16_f32 v63, v30, v31
	v_cvt_pk_bf16_f32 v56, v24, v25
	v_cvt_pk_bf16_f32 v57, v26, v27
	v_cvt_pk_bf16_f32 v58, v20, v21
	s_waitcnt lgkmcnt(3)
	v_mfma_f32_16x16x32_bf16 v[226:229], v[230:233], v[60:63], 0
	ds_read_b128 v[230:233], v234 offset:4352
	v_cvt_pk_bf16_f32 v59, v22, v23
	v_cvt_pk_bf16_f32 v52, v16, v17
	v_cvt_pk_bf16_f32 v53, v18, v19
	s_waitcnt lgkmcnt(3)
	v_mfma_f32_16x16x32_bf16 v[226:229], v[236:239], v[56:59], v[226:229]
	ds_read_b128 v[236:239], v234 offset:4416
	v_cvt_pk_bf16_f32 v54, v12, v13
	v_cvt_pk_bf16_f32 v55, v14, v15
	v_cvt_pk_bf16_f32 v48, v8, v9
	v_cvt_pk_bf16_f32 v49, v10, v11
	v_cvt_pk_bf16_f32 v50, v4, v5
	v_cvt_pk_bf16_f32 v51, v6, v7
	s_add_i32 s6, s6, s15
	s_waitcnt lgkmcnt(3)
	v_mfma_f32_16x16x32_bf16 v[226:229], v[248:251], v[52:55], v[226:229]
	ds_read_b128 v[248:251], v234 offset:4480
	s_lshl_b32 s6, s6, 6
	s_waitcnt lgkmcnt(3)
	v_mfma_f32_16x16x32_bf16 v[226:229], v[252:255], v[48:51], v[226:229]
	ds_read_b128 v[252:255], v234 offset:4544
	v_add_u32_e32 v240, s6, v134
	v_ashrrev_i32_e32 v241, 31, v240
	s_nop 5
	v_add_f32_e32 v226, v224, v226
	v_lshlrev_b64 v[224:225], 10, v[240:241]
	v_lshl_add_u64 v[224:225], v[76:77], 0, v[224:225]
	global_store_dword v[224:225], v226, off
	v_add_u32_e32 v224, s6, v135
	v_ashrrev_i32_e32 v225, 31, v224
	v_lshlrev_b64 v[224:225], 10, v[224:225]
	v_add_f32_e32 v223, v223, v227
	v_lshl_add_u64 v[224:225], v[76:77], 0, v[224:225]
	global_store_dword v[224:225], v223, off
	v_add_u32_e32 v224, s6, v143
	v_ashrrev_i32_e32 v225, 31, v224
	v_add_f32_e32 v226, v222, v228
	v_lshlrev_b64 v[222:223], 10, v[224:225]
	v_lshl_add_u64 v[222:223], v[76:77], 0, v[222:223]
	global_store_dword v[222:223], v226, off
	v_add_u32_e32 v222, s6, v145
	v_ashrrev_i32_e32 v223, 31, v222
	v_lshlrev_b64 v[222:223], 10, v[222:223]
	v_add_f32_e32 v221, v221, v229
	v_lshl_add_u64 v[222:223], v[76:77], 0, v[222:223]
	global_store_dword v[222:223], v221, off
	s_waitcnt lgkmcnt(3)
	v_mfma_f32_16x16x32_bf16 v[222:225], v[230:233], v[60:63], 0
	ds_read_b128 v[230:233], v234 offset:8704
	s_waitcnt lgkmcnt(3)
	v_mfma_f32_16x16x32_bf16 v[222:225], v[236:239], v[56:59], v[222:225]
	ds_read_b128 v[236:239], v234 offset:8768
	s_waitcnt lgkmcnt(3)
	v_mfma_f32_16x16x32_bf16 v[222:225], v[248:251], v[52:55], v[222:225]
	ds_read_b128 v[248:251], v234 offset:8832
	s_waitcnt lgkmcnt(3)
	v_mfma_f32_16x16x32_bf16 v[222:225], v[252:255], v[48:51], v[222:225]
	ds_read_b128 v[252:255], v234 offset:8896
	v_add_u32_e32 v226, s6, v146
	v_ashrrev_i32_e32 v227, 31, v226
	v_lshlrev_b64 v[226:227], 10, v[226:227]
	s_nop 4
	v_add_f32_e32 v218, v218, v222
	v_add_u32_e32 v222, s6, v147
	v_add_f32_e32 v217, v217, v223
	v_ashrrev_i32_e32 v223, 31, v222
	v_lshlrev_b64 v[222:223], 10, v[222:223]
	v_lshl_add_u64 v[226:227], v[76:77], 0, v[226:227]
	v_lshl_add_u64 v[222:223], v[76:77], 0, v[222:223]
	global_store_dword v[226:227], v218, off
	global_store_dword v[222:223], v217, off
	v_add_u32_e32 v222, s6, v148
	v_ashrrev_i32_e32 v223, 31, v222
	v_add_f32_e32 v218, v216, v224
	v_lshlrev_b64 v[216:217], 10, v[222:223]
	v_add_f32_e32 v214, v214, v225
	s_waitcnt lgkmcnt(3)
	v_mfma_f32_16x16x32_bf16 v[222:225], v[230:233], v[60:63], 0
	ds_read_b128 v[230:233], v234 offset:13056
	v_lshl_add_u64 v[216:217], v[76:77], 0, v[216:217]
	global_store_dword v[216:217], v218, off
	v_add_u32_e32 v216, s6, v149
	s_waitcnt lgkmcnt(3)
	v_mfma_f32_16x16x32_bf16 v[222:225], v[236:239], v[56:59], v[222:225]
	ds_read_b128 v[236:239], v234 offset:13120
	v_ashrrev_i32_e32 v217, 31, v216
	v_lshlrev_b64 v[216:217], 10, v[216:217]
	s_waitcnt lgkmcnt(3)
	v_mfma_f32_16x16x32_bf16 v[222:225], v[248:251], v[52:55], v[222:225]
	ds_read_b128 v[248:251], v234 offset:13184
	v_lshl_add_u64 v[216:217], v[76:77], 0, v[216:217]
	global_store_dword v[216:217], v214, off
	s_waitcnt lgkmcnt(3)
	v_mfma_f32_16x16x32_bf16 v[222:225], v[252:255], v[48:51], v[222:225]
	ds_read_b128 v[252:255], v234 offset:13248
	v_add_u32_e32 v216, s6, v150
	v_ashrrev_i32_e32 v217, 31, v216
	v_lshlrev_b64 v[216:217], 10, v[216:217]
	s_nop 4
	v_add_f32_e32 v211, v211, v222
	v_lshl_add_u64 v[216:217], v[76:77], 0, v[216:217]
	global_store_dword v[216:217], v211, off
	v_add_u32_e32 v216, s6, v151
	v_ashrrev_i32_e32 v217, 31, v216
	v_lshlrev_b64 v[216:217], 10, v[216:217]
	v_add_f32_e32 v209, v209, v223
	v_lshl_add_u64 v[216:217], v[76:77], 0, v[216:217]
	global_store_dword v[216:217], v209, off
	v_add_f32_e32 v207, v207, v224
	v_add_f32_e32 v209, v206, v225
	s_waitcnt lgkmcnt(3)
	v_mfma_f32_16x16x32_bf16 v[60:63], v[230:233], v[60:63], 0
	v_add_u32_e32 v216, s6, v152
	v_ashrrev_i32_e32 v217, 31, v216
	s_waitcnt lgkmcnt(2)
	v_mfma_f32_16x16x32_bf16 v[56:59], v[236:239], v[56:59], v[60:63]
	s_nop 2
	v_lshlrev_b64 v[216:217], 10, v[216:217]
	v_lshl_add_u64 v[216:217], v[76:77], 0, v[216:217]
	s_waitcnt lgkmcnt(1)
	v_mfma_f32_16x16x32_bf16 v[52:55], v[248:251], v[52:55], v[56:59]
	s_nop 2
	global_store_dword v[216:217], v207, off
	v_add_u32_e32 v216, s6, v153
	s_waitcnt lgkmcnt(0)
	v_mfma_f32_16x16x32_bf16 v[48:51], v[252:255], v[48:51], v[52:55]
	s_nop 2
	v_add_u32_e32 v52, s6, v154
	v_ashrrev_i32_e32 v217, 31, v216
	v_ashrrev_i32_e32 v53, 31, v52
	v_lshlrev_b64 v[206:207], 10, v[216:217]
	v_lshlrev_b64 v[52:53], 10, v[52:53]
	v_lshl_add_u64 v[206:207], v[76:77], 0, v[206:207]
	v_add_f32_e32 v48, v161, v48
	v_lshl_add_u64 v[52:53], v[76:77], 0, v[52:53]
	global_store_dword v[206:207], v209, off
	global_store_dword v[52:53], v48, off
	v_add_u32_e32 v48, s6, v155
	v_add_f32_e32 v52, v160, v49
	v_ashrrev_i32_e32 v49, 31, v48
	v_lshlrev_b64 v[48:49], 10, v[48:49]
	v_lshl_add_u64 v[48:49], v[76:77], 0, v[48:49]
	global_store_dword v[48:49], v52, off
	v_add_u32_e32 v48, s6, v156
	v_ashrrev_i32_e32 v49, 31, v48
	v_lshlrev_b64 v[48:49], 10, v[48:49]
	v_add_f32_e32 v50, v159, v50
	v_lshl_add_u64 v[48:49], v[76:77], 0, v[48:49]
	global_store_dword v[48:49], v50, off
	v_add_u32_e32 v48, s6, v136
	v_ashrrev_i32_e32 v49, 31, v48
	v_lshlrev_b64 v[48:49], 10, v[48:49]
	v_add_f32_e32 v50, v158, v51
	v_lshl_add_u64 v[48:49], v[76:77], 0, v[48:49]
	global_store_dword v[48:49], v50, off
	s_andn2_b64 vcc, exec, s[4:5]
	s_cbranch_vccnz .LBB0_317
	s_bitcmp1_b32 s18, 0
	s_cselect_b32 s4, 0x4400, 0
	v_add3_u32 v51, s4, v128, v129
	v_add3_u32 v48, s4, v132, v129
	v_add3_u32 v49, s4, v131, v129
	v_add3_u32 v50, s4, v130, v129
	s_waitcnt vmcnt(44)
	ds_write_b128 v51, v[32:35]
	s_waitcnt vmcnt(43)
	ds_write_b128 v50, v[36:39]
	s_waitcnt vmcnt(42)
	ds_write_b128 v49, v[40:43]
	s_waitcnt vmcnt(41)
	ds_write_b128 v48, v[44:47]
	s_branch .LBB0_317

.LBB0_332:
	v_mul_f32_e32 v50, 0x3fb8aa3b, v52
	s_and_b64 s[20:21], s[68:69], exec
	v_exp_f32_e32 v92, v50
	s_cselect_b32 s17, s18, s14
	s_bitcmp1_b32 s18, 0
	s_cselect_b32 s18, 0x9000, 0
	v_add_u32_e32 v128, s18, v110
	ds_read_b128 v[204:207], v128
	ds_read_b128 v[208:211], v128 offset:9216
	ds_read_b128 v[212:215], v128 offset:64
	ds_read_b128 v[216:219], v128 offset:9280
	ds_read_b128 v[220:223], v128 offset:2304
	ds_read_b128 v[224:227], v128 offset:11520
	ds_read_b128 v[228:231], v128 offset:2368
	ds_read_b128 v[232:235], v128 offset:11584
	v_cvt_pk_bf16_f32 v64, v12, v13
	v_cvt_pk_bf16_f32 v65, v14, v15
	v_cvt_pk_bf16_f32 v66, v0, v1
	v_cvt_pk_bf16_f32 v67, v2, v3
	s_nop 0
	s_waitcnt lgkmcnt(7)
	v_mfma_f32_16x16x32_bf16 v[56:59], v[204:207], v[64:67], 0
	ds_read_b128 v[204:207], v128 offset:4608
	v_cvt_pk_bf16_f32 v52, v8, v9
	v_cvt_pk_bf16_f32 v53, v10, v11
	v_cvt_pk_bf16_f32 v54, v4, v5
	v_cvt_pk_bf16_f32 v55, v6, v7
	s_waitcnt lgkmcnt(7)
	v_mfma_f32_16x16x32_bf16 v[130:133], v[208:211], v[64:67], 0
	ds_read_b128 v[208:211], v128 offset:13824
	v_lshlrev_b32_e32 v50, 16, v48
	v_and_b32_e32 v51, 0xffff0000, v48
	v_lshlrev_b32_e32 v48, 16, v49
	s_waitcnt lgkmcnt(7)
	v_mfma_f32_16x16x32_bf16 v[146:149], v[212:215], v[52:55], v[56:59]
	ds_read_b128 v[212:215], v128 offset:4672
	v_and_b32_e32 v49, 0xffff0000, v49
	v_lshlrev_b32_e32 v62, 16, v60
	v_and_b32_e32 v63, 0xffff0000, v60
	s_waitcnt lgkmcnt(7)
	v_mfma_f32_16x16x32_bf16 v[56:59], v[216:219], v[52:55], v[130:133]
	ds_read_b128 v[216:219], v128 offset:13888
	v_lshlrev_b32_e32 v60, 16, v61
	s_nop 1
	v_pk_add_f32 v[134:135], v[50:51], v[146:147] neg_lo:[0,1] neg_hi:[0,1]
	v_pk_add_f32 v[154:155], v[48:49], v[148:149] neg_lo:[0,1] neg_hi:[0,1]
	s_waitcnt lgkmcnt(7)
	v_mfma_f32_16x16x32_bf16 v[48:51], v[220:223], v[64:67], 0
	ds_read_b128 v[220:223], v128 offset:6912
	v_and_b32_e32 v61, 0xffff0000, v61
	v_pk_mul_f32 v[12:13], v[12:13], v[92:93] op_sel_hi:[1,0]
	s_waitcnt lgkmcnt(7)
	v_mfma_f32_16x16x32_bf16 v[130:133], v[224:227], v[64:67], 0
	ds_read_b128 v[224:227], v128 offset:16128
	v_mul_f32_e64 v14, v14, v92
	v_mul_f32_e64 v15, v15, v92
	v_pk_mul_f32 v[0:1], v[0:1], v[92:93] op_sel_hi:[1,0]
	v_pk_mul_f32 v[2:3], v[2:3], v[92:93] op_sel_hi:[1,0]
	s_waitcnt lgkmcnt(7)
	v_mfma_f32_16x16x32_bf16 v[146:149], v[228:231], v[52:55], v[48:51]
	ds_read_b128 v[228:231], v128 offset:6976
	v_mul_f32_e64 v8, v8, v92
	v_mul_f32_e64 v9, v9, v92
	v_pk_mul_f32 v[10:11], v[10:11], v[92:93] op_sel_hi:[1,0]
	v_pk_mul_f32 v[4:5], v[4:5], v[92:93] op_sel_hi:[1,0]
	s_waitcnt lgkmcnt(7)
	v_mfma_f32_16x16x32_bf16 v[48:51], v[232:235], v[52:55], v[130:133]
	ds_read_b128 v[232:235], v128 offset:16192
	v_mul_f32_e64 v6, v6, v92
	v_mul_f32_e64 v7, v7, v92
	v_pk_add_f32 v[156:157], v[62:63], v[146:147] neg_lo:[0,1] neg_hi:[0,1]
	v_pk_add_f32 v[158:159], v[60:61], v[148:149] neg_lo:[0,1] neg_hi:[0,1]
	s_waitcnt lgkmcnt(7)
	v_mfma_f32_16x16x32_bf16 v[60:63], v[204:207], v[64:67], 0
	ds_read_b128 v[204:207], v128 offset:18432
	s_add_i32 s17, s17, s13
	s_lshl_b32 s17, s17, 6
	s_waitcnt lgkmcnt(7)
	v_mfma_f32_16x16x32_bf16 v[130:133], v[208:211], v[64:67], 0
	ds_read_b128 v[208:211], v128 offset:27648
	s_waitcnt lgkmcnt(7)
	v_mfma_f32_16x16x32_bf16 v[146:149], v[212:215], v[52:55], v[60:63]
	ds_read_b128 v[212:215], v128 offset:18496
	s_waitcnt lgkmcnt(7)
	v_mfma_f32_16x16x32_bf16 v[60:63], v[216:219], v[52:55], v[130:133]
	ds_read_b128 v[216:219], v128 offset:27712
	s_nop 3
	v_lshlrev_b32_e32 v130, 16, v90
	v_and_b32_e32 v131, 0xffff0000, v90
	v_lshlrev_b32_e32 v90, 16, v91
	v_and_b32_e32 v91, 0xffff0000, v91
	v_pk_add_f32 v[160:161], v[130:131], v[146:147] neg_lo:[0,1] neg_hi:[0,1]
	v_pk_add_f32 v[90:91], v[90:91], v[148:149] neg_lo:[0,1] neg_hi:[0,1]
	s_waitcnt lgkmcnt(7)
	v_mfma_f32_16x16x32_bf16 v[130:133], v[220:223], v[64:67], 0
	ds_read_b128 v[220:223], v128 offset:20736
	s_waitcnt lgkmcnt(7)
	v_mfma_f32_16x16x32_bf16 v[64:67], v[224:227], v[64:67], 0
	ds_read_b128 v[224:227], v128 offset:29952
	s_waitcnt lgkmcnt(7)
	v_mfma_f32_16x16x32_bf16 v[130:133], v[228:231], v[52:55], v[130:133]
	ds_read_b128 v[228:231], v128 offset:20800
	s_waitcnt lgkmcnt(7)
	v_mfma_f32_16x16x32_bf16 v[52:55], v[232:235], v[52:55], v[64:67]
	ds_read_b128 v[232:235], v128 offset:30016
	s_nop 2
	v_lshlrev_b32_e32 v64, 16, v88
	v_and_b32_e32 v65, 0xffff0000, v88
	s_nop 0
	v_pk_add_f32 v[130:131], v[64:65], v[130:131] neg_lo:[0,1] neg_hi:[0,1]
	v_lshlrev_b32_e32 v64, 16, v89
	v_and_b32_e32 v65, 0xffff0000, v89
	v_pk_add_f32 v[132:133], v[64:65], v[132:133] neg_lo:[0,1] neg_hi:[0,1]
	v_cvt_pk_bf16_f32 v89, v90, v91
	v_cvt_pk_bf16_f32 v90, v130, v131
	v_cvt_pk_bf16_f32 v91, v132, v133
	v_cvt_pk_bf16_f32 v64, v134, v135
	v_cvt_pk_bf16_f32 v65, v154, v155
	v_cvt_pk_bf16_f32 v66, v156, v157
	v_cvt_pk_bf16_f32 v67, v158, v159
	v_cvt_pk_bf16_f32 v88, v160, v161
	s_waitcnt lgkmcnt(7)
	v_mfma_f32_16x16x32_bf16 v[56:59], v[204:207], v[64:67], v[56:59]
	ds_read_b128 v[204:207], v128 offset:23040
	s_waitcnt lgkmcnt(7)
	v_mfma_f32_16x16x32_bf16 v[12:15], v[208:211], v[64:67], v[12:15]
	ds_read_b128 v[208:211], v128 offset:32256
	s_waitcnt lgkmcnt(7)
	v_mfma_f32_16x16x32_bf16 v[56:59], v[212:215], v[88:91], v[56:59]
	ds_read_b128 v[212:215], v128 offset:23104
	s_waitcnt lgkmcnt(7)
	v_mfma_f32_16x16x32_bf16 v[12:15], v[216:219], v[88:91], v[12:15]
	ds_read_b128 v[216:219], v128 offset:32320
	s_nop 3
	v_cvt_pk_bf16_f32 v56, v56, s0
	v_cvt_pk_bf16_f32 v58, v58, s0
	s_waitcnt lgkmcnt(7)
	v_mfma_f32_16x16x32_bf16 v[48:51], v[220:223], v[64:67], v[48:51]
	ds_read_b128 v[220:223], v128 offset:25344
	s_waitcnt lgkmcnt(7)
	v_mfma_f32_16x16x32_bf16 v[0:3], v[224:227], v[64:67], v[0:3]
	ds_read_b128 v[224:227], v128 offset:34560
	s_waitcnt lgkmcnt(7)
	v_mfma_f32_16x16x32_bf16 v[48:51], v[228:231], v[88:91], v[48:51]
	ds_read_b128 v[228:231], v128 offset:25408
	s_waitcnt lgkmcnt(7)
	v_mfma_f32_16x16x32_bf16 v[0:3], v[232:235], v[88:91], v[0:3]
	ds_read_b128 v[232:235], v128 offset:34624
	s_nop 3
	v_cvt_pk_bf16_f32 v48, v48, s0
	v_cvt_pk_bf16_f32 v50, v50, s0
	s_waitcnt lgkmcnt(7)
	v_mfma_f32_16x16x32_bf16 v[60:63], v[204:207], v[64:67], v[60:63]
	s_waitcnt lgkmcnt(6)
	v_mfma_f32_16x16x32_bf16 v[8:11], v[208:211], v[64:67], v[8:11]
	s_waitcnt lgkmcnt(5)
	v_mfma_f32_16x16x32_bf16 v[60:63], v[212:215], v[88:91], v[60:63]
	s_waitcnt lgkmcnt(4)
	v_mfma_f32_16x16x32_bf16 v[8:11], v[216:219], v[88:91], v[8:11]
	s_waitcnt lgkmcnt(3)
	v_mfma_f32_16x16x32_bf16 v[52:55], v[220:223], v[64:67], v[52:55]
	s_waitcnt lgkmcnt(2)
	v_mfma_f32_16x16x32_bf16 v[4:7], v[224:227], v[64:67], v[4:7]
	s_waitcnt lgkmcnt(1)
	v_mfma_f32_16x16x32_bf16 v[52:55], v[228:231], v[88:91], v[52:55]
	v_or_b32_e32 v64, s17, v93
	v_ashrrev_i32_e32 v65, 31, v64
	v_lshlrev_b64 v[64:65], 9, v[64:65]
	v_lshl_add_u64 v[64:65], v[76:77], 0, v[64:65]
	global_store_short v[64:65], v56, off
	v_or_b32_e32 v56, s17, v112
	v_cvt_pk_bf16_f32 v64, v57, s0
	v_ashrrev_i32_e32 v57, 31, v56
	v_lshlrev_b64 v[56:57], 9, v[56:57]
	v_lshl_add_u64 v[56:57], v[76:77], 0, v[56:57]
	global_store_short v[56:57], v64, off
	v_or_b32_e32 v56, s17, v113
	v_ashrrev_i32_e32 v57, 31, v56
	v_lshlrev_b64 v[56:57], 9, v[56:57]
	v_lshl_add_u64 v[56:57], v[76:77], 0, v[56:57]
	global_store_short v[56:57], v58, off
	v_or_b32_e32 v56, s17, v114
	v_ashrrev_i32_e32 v57, 31, v56
	v_lshlrev_b64 v[56:57], 9, v[56:57]
	v_cvt_pk_bf16_f32 v58, v59, s0
	v_lshl_add_u64 v[56:57], v[76:77], 0, v[56:57]
	global_store_short v[56:57], v58, off
	v_or_b32_e32 v56, s17, v115
	v_ashrrev_i32_e32 v57, 31, v56
	v_lshlrev_b64 v[56:57], 9, v[56:57]
	v_lshl_add_u64 v[56:57], v[76:77], 0, v[56:57]
	global_store_short v[56:57], v48, off
	v_or_b32_e32 v48, s17, v116
	v_cvt_pk_bf16_f32 v56, v49, s0
	v_ashrrev_i32_e32 v49, 31, v48
	v_lshlrev_b64 v[48:49], 9, v[48:49]
	v_lshl_add_u64 v[48:49], v[76:77], 0, v[48:49]
	global_store_short v[48:49], v56, off
	v_or_b32_e32 v48, s17, v117
	v_ashrrev_i32_e32 v49, 31, v48
	v_lshlrev_b64 v[48:49], 9, v[48:49]
	v_lshl_add_u64 v[48:49], v[76:77], 0, v[48:49]
	global_store_short v[48:49], v50, off
	v_or_b32_e32 v48, s17, v118
	v_ashrrev_i32_e32 v49, 31, v48
	v_lshlrev_b64 v[48:49], 9, v[48:49]
	v_cvt_pk_bf16_f32 v50, v51, s0
	v_lshl_add_u64 v[48:49], v[76:77], 0, v[48:49]
	global_store_short v[48:49], v50, off
	v_or_b32_e32 v48, s17, v119
	v_ashrrev_i32_e32 v49, 31, v48
	v_lshlrev_b64 v[48:49], 9, v[48:49]
	v_cvt_pk_bf16_f32 v50, v60, s0
	v_lshl_add_u64 v[48:49], v[76:77], 0, v[48:49]
	global_store_short v[48:49], v50, off
	v_or_b32_e32 v48, s17, v120
	v_ashrrev_i32_e32 v49, 31, v48
	v_lshlrev_b64 v[48:49], 9, v[48:49]
	v_cvt_pk_bf16_f32 v50, v61, s0
	v_lshl_add_u64 v[48:49], v[76:77], 0, v[48:49]
	global_store_short v[48:49], v50, off
	v_or_b32_e32 v48, s17, v121
	v_ashrrev_i32_e32 v49, 31, v48
	v_lshlrev_b64 v[48:49], 9, v[48:49]
	v_cvt_pk_bf16_f32 v50, v62, s0
	v_lshl_add_u64 v[48:49], v[76:77], 0, v[48:49]
	global_store_short v[48:49], v50, off
	v_or_b32_e32 v48, s17, v122
	v_ashrrev_i32_e32 v49, 31, v48
	v_lshlrev_b64 v[48:49], 9, v[48:49]
	v_cvt_pk_bf16_f32 v50, v63, s0
	v_lshl_add_u64 v[48:49], v[76:77], 0, v[48:49]
	global_store_short v[48:49], v50, off
	v_or_b32_e32 v48, s17, v123
	v_ashrrev_i32_e32 v49, 31, v48
	v_lshlrev_b64 v[48:49], 9, v[48:49]
	v_cvt_pk_bf16_f32 v50, v52, s0
	v_lshl_add_u64 v[48:49], v[76:77], 0, v[48:49]
	global_store_short v[48:49], v50, off
	v_or_b32_e32 v48, s17, v124
	v_ashrrev_i32_e32 v49, 31, v48
	v_lshlrev_b64 v[48:49], 9, v[48:49]
	v_cvt_pk_bf16_f32 v50, v53, s0
	v_lshl_add_u64 v[48:49], v[76:77], 0, v[48:49]
	global_store_short v[48:49], v50, off
	v_or_b32_e32 v48, s17, v125
	v_ashrrev_i32_e32 v49, 31, v48
	v_lshlrev_b64 v[48:49], 9, v[48:49]
	v_cvt_pk_bf16_f32 v50, v54, s0
	v_lshl_add_u64 v[48:49], v[76:77], 0, v[48:49]
	s_waitcnt lgkmcnt(0)
	v_mfma_f32_16x16x32_bf16 v[4:7], v[232:235], v[88:91], v[4:7]
	global_store_short v[48:49], v50, off
	v_or_b32_e32 v48, s17, v126
	v_ashrrev_i32_e32 v49, 31, v48
	v_lshlrev_b64 v[48:49], 9, v[48:49]
	v_cvt_pk_bf16_f32 v50, v55, s0
	v_lshl_add_u64 v[48:49], v[76:77], 0, v[48:49]
	global_store_short v[48:49], v50, off
	s_andn2_b64 vcc, exec, s[4:5]
	s_cbranch_vccnz .LBB0_329
	s_bitcmp1_b32 s16, 0
	s_cselect_b32 s4, 0x9000, 0
	v_add3_u32 v48, s4, v108, v109
	v_add3_u32 v49, s4, v111, v109
	s_waitcnt vmcnt(28)
	ds_write_b128 v48, v[16:19]
	s_waitcnt vmcnt(27)
	ds_write_b128 v49, v[20:23]
	s_waitcnt vmcnt(26)
	ds_write_b128 v48, v[24:27] offset:9216
	s_waitcnt vmcnt(25)
	ds_write_b128 v49, v[28:31] offset:9216
	s_waitcnt vmcnt(24)
	ds_write_b128 v48, v[32:35] offset:18432
	s_waitcnt vmcnt(23)
	ds_write_b128 v49, v[36:39] offset:18432
	s_waitcnt vmcnt(22)
	ds_write_b128 v48, v[40:43] offset:27648
	s_waitcnt vmcnt(21)
	ds_write_b128 v49, v[44:47] offset:27648
	s_branch .LBB0_329
